# raised issue priority for the 16-row-window pool task's K loop (waves 6,7)
# baseline (speedup 1.0000x reference)
.LBB0_332:
	s_or_b64 exec, exec, s[6:7]
	s_waitcnt lgkmcnt(0)
	s_setprio 2
	global_load_dwordx4 v[82:85], v[144:145], off offset:512
	global_load_dwordx4 v[86:89], v[146:147], off offset:512
	global_load_dwordx4 v[90:93], v[148:149], off offset:512
	global_load_dwordx4 v[94:97], v[150:151], off offset:512
	global_load_dwordx4 v[112:115], v[144:145], off offset:1024
	global_load_dwordx4 v[116:119], v[146:147], off offset:1024
	global_load_dwordx4 v[122:125], v[148:149], off offset:1024
	global_load_dwordx4 v[126:129], v[150:151], off offset:1024
	v_or_b32_e32 v2, s28, v1
	v_min_u32_e32 v3, 15, v2
	v_add_u32_e32 v3, 1, v3
	v_cvt_f32_ubyte0_e32 v3, v3
	v_div_scale_f32 v4, s[6:7], v3, v3, 1.0
	v_rcp_f32_e32 v5, v4
	s_ashr_i32 s8, s30, 6
	s_mul_i32 s10, s8, 15
	v_cmp_lt_u32_e64 s[6:7], s41, v2
	v_fma_f32 v6, -v4, v5, 1.0
	v_fmac_f32_e32 v5, v6, v5
	v_div_scale_f32 v6, vcc, 1.0, v3, 1.0
	v_mul_f32_e32 v7, v6, v5
	v_fma_f32 v8, -v4, v7, v6
	v_fmac_f32_e32 v7, v8, v5
	v_fma_f32 v4, -v4, v7, v6
	v_div_fmas_f32 v4, v4, v5, v7
	v_div_fixup_f32 v159, v4, v3, 1.0
	s_ashr_i32 s11, s10, 31
	v_add_u32_e32 v2, 0xfffff80f, v2
	v_mov_b32_e32 v3, v155
	v_lshl_add_u64 v[2:3], v[2:3], 0, s[10:11]
	v_lshlrev_b64 v[2:3], 11, v[2:3]
	v_lshl_add_u64 v[2:3], s[70:71], 0, v[2:3]
	v_mov_b32_e32 v163, v155
	v_lshl_add_u64 v[2:3], v[2:3], 0, v[162:163]
	v_lshl_add_u64 v[192:193], v[2:3], 0, s[16:17]
	v_mov_b32_e32 v2, 0
	s_mov_b32 s49, 0
	s_mov_b64 s[10:11], 0
	v_mov_b32_e32 v3, v2
	v_mov_b32_e32 v4, v2
	v_mov_b32_e32 v5, v2
	v_mov_b32_e32 v6, v2
	v_mov_b32_e32 v7, v2
	v_mov_b32_e32 v8, v2
	v_mov_b32_e32 v9, v2
	v_mov_b32_e32 v10, v2
	v_mov_b32_e32 v11, v2
	v_mov_b32_e32 v12, v2
	v_mov_b32_e32 v13, v2
	v_mov_b32_e32 v14, v2
	v_mov_b32_e32 v15, v2
	v_mov_b32_e32 v16, v2
	v_mov_b32_e32 v17, v2
	v_mov_b32_e32 v18, v2
	v_mov_b32_e32 v19, v2
	v_mov_b32_e32 v20, v2
	v_mov_b32_e32 v21, v2
	v_mov_b32_e32 v22, v2
	v_mov_b32_e32 v23, v2
	v_mov_b32_e32 v24, v2
	v_mov_b32_e32 v25, v2
	v_mov_b32_e32 v26, v2
	v_mov_b32_e32 v27, v2
	v_mov_b32_e32 v28, v2
	v_mov_b32_e32 v29, v2
	v_mov_b32_e32 v30, v2
	v_mov_b32_e32 v31, v2
	v_mov_b32_e32 v32, v2
	v_mov_b32_e32 v33, v2
	v_mov_b32_e32 v34, v2
	v_mov_b32_e32 v35, v2
	v_mov_b32_e32 v36, v2
	v_mov_b32_e32 v37, v2
	v_mov_b32_e32 v38, v2
	v_mov_b32_e32 v39, v2
	v_mov_b32_e32 v40, v2
	v_mov_b32_e32 v41, v2
	v_mov_b32_e32 v42, v2
	v_mov_b32_e32 v43, v2
	v_mov_b32_e32 v44, v2
	v_mov_b32_e32 v45, v2
	v_mov_b32_e32 v46, v2
	v_mov_b32_e32 v47, v2
	v_mov_b32_e32 v48, v2
	v_mov_b32_e32 v49, v2
	v_mov_b32_e32 v50, v2
	v_mov_b32_e32 v51, v2
	v_mov_b32_e32 v52, v2
	v_mov_b32_e32 v53, v2
	v_mov_b32_e32 v54, v2
	v_mov_b32_e32 v55, v2
	v_mov_b32_e32 v56, v2
	v_mov_b32_e32 v57, v2
	v_mov_b32_e32 v58, v2
	v_mov_b32_e32 v59, v2
	v_mov_b32_e32 v60, v2
	v_mov_b32_e32 v61, v2
	v_mov_b32_e32 v62, v2
	v_mov_b32_e32 v63, v2
	v_mov_b32_e32 v64, v2
	v_mov_b32_e32 v65, v2
	v_lshl_add_u32 v163, v197, 1, v214
	ds_read_b128 v[222:225], v163 offset:4080
	ds_read_b128 v[226:229], v163 offset:3808
	ds_read_b128 v[230:233], v163 offset:3536
	ds_read_b128 v[234:237], v163 offset:3264
	ds_read_b128 v[238:241], v163 offset:2992
	ds_read_b128 v[242:245], v163 offset:2720
	ds_read_b128 v[248:251], v163 offset:2448
	ds_read_b128 v[252:255], v163 offset:2176
	s_waitcnt lgkmcnt(7)
	v_lshlrev_b32_e32 v98, 16, v222
	v_and_b32_e32 v99, 0xffff0000, v222
	v_lshlrev_b32_e32 v100, 16, v223
	v_and_b32_e32 v101, 0xffff0000, v223
	v_lshlrev_b32_e32 v102, 16, v224
	v_and_b32_e32 v103, 0xffff0000, v224
	v_lshlrev_b32_e32 v104, 16, v225
	v_and_b32_e32 v105, 0xffff0000, v225
	ds_read_b128 v[222:225], v163 offset:1904
	s_waitcnt lgkmcnt(7)
	v_lshlrev_b32_e32 v216, 16, v226
	v_and_b32_e32 v217, 0xffff0000, v226
	v_pk_add_f32 v[106:107], v[98:99], v[216:217]
	v_lshlrev_b32_e32 v216, 16, v227
	v_and_b32_e32 v217, 0xffff0000, v227
	v_pk_add_f32 v[108:109], v[100:101], v[216:217]
	v_lshlrev_b32_e32 v216, 16, v228
	v_and_b32_e32 v217, 0xffff0000, v228
	v_pk_add_f32 v[218:219], v[102:103], v[216:217]
	v_lshlrev_b32_e32 v216, 16, v229
	v_and_b32_e32 v217, 0xffff0000, v229
	v_pk_add_f32 v[220:221], v[104:105], v[216:217]
	ds_read_b128 v[226:229], v163 offset:1632
	s_waitcnt lgkmcnt(7)
	v_lshlrev_b32_e32 v216, 16, v230
	v_and_b32_e32 v217, 0xffff0000, v230
	v_pk_add_f32 v[106:107], v[106:107], v[216:217]
	v_lshlrev_b32_e32 v216, 16, v231
	v_and_b32_e32 v217, 0xffff0000, v231
	v_pk_add_f32 v[108:109], v[108:109], v[216:217]
	v_lshlrev_b32_e32 v216, 16, v232
	v_and_b32_e32 v217, 0xffff0000, v232
	v_pk_add_f32 v[218:219], v[218:219], v[216:217]
	v_lshlrev_b32_e32 v216, 16, v233
	v_and_b32_e32 v217, 0xffff0000, v233
	v_pk_add_f32 v[220:221], v[220:221], v[216:217]
	ds_read_b128 v[230:233], v163 offset:1360
	s_waitcnt lgkmcnt(7)
	v_lshlrev_b32_e32 v216, 16, v234
	v_and_b32_e32 v217, 0xffff0000, v234
	v_pk_add_f32 v[106:107], v[106:107], v[216:217]
	v_lshlrev_b32_e32 v216, 16, v235
	v_and_b32_e32 v217, 0xffff0000, v235
	v_pk_add_f32 v[108:109], v[108:109], v[216:217]
	v_lshlrev_b32_e32 v216, 16, v236
	v_and_b32_e32 v217, 0xffff0000, v236
	v_pk_add_f32 v[218:219], v[218:219], v[216:217]
	v_lshlrev_b32_e32 v216, 16, v237
	v_and_b32_e32 v217, 0xffff0000, v237
	v_pk_add_f32 v[220:221], v[220:221], v[216:217]
	ds_read_b128 v[234:237], v163 offset:1088
	s_waitcnt lgkmcnt(7)
	v_lshlrev_b32_e32 v216, 16, v238
	v_and_b32_e32 v217, 0xffff0000, v238
	v_pk_add_f32 v[106:107], v[106:107], v[216:217]
	v_lshlrev_b32_e32 v216, 16, v239
	v_and_b32_e32 v217, 0xffff0000, v239
	v_pk_add_f32 v[108:109], v[108:109], v[216:217]
	v_lshlrev_b32_e32 v216, 16, v240
	v_and_b32_e32 v217, 0xffff0000, v240
	v_pk_add_f32 v[218:219], v[218:219], v[216:217]
	v_lshlrev_b32_e32 v216, 16, v241
	v_and_b32_e32 v217, 0xffff0000, v241
	v_pk_add_f32 v[220:221], v[220:221], v[216:217]
	ds_read_b128 v[238:241], v163 offset:816
	s_waitcnt lgkmcnt(7)
	v_lshlrev_b32_e32 v216, 16, v242
	v_and_b32_e32 v217, 0xffff0000, v242
	v_pk_add_f32 v[106:107], v[106:107], v[216:217]
	v_lshlrev_b32_e32 v216, 16, v243
	v_and_b32_e32 v217, 0xffff0000, v243
	v_pk_add_f32 v[108:109], v[108:109], v[216:217]
	v_lshlrev_b32_e32 v216, 16, v244
	v_and_b32_e32 v217, 0xffff0000, v244
	v_pk_add_f32 v[218:219], v[218:219], v[216:217]
	v_lshlrev_b32_e32 v216, 16, v245
	v_and_b32_e32 v217, 0xffff0000, v245
	v_pk_add_f32 v[220:221], v[220:221], v[216:217]
	ds_read_b128 v[242:245], v163 offset:544
	s_waitcnt lgkmcnt(7)
	v_lshlrev_b32_e32 v216, 16, v248
	v_and_b32_e32 v217, 0xffff0000, v248
	v_pk_add_f32 v[106:107], v[106:107], v[216:217]
	v_lshlrev_b32_e32 v216, 16, v249
	v_and_b32_e32 v217, 0xffff0000, v249
	v_pk_add_f32 v[108:109], v[108:109], v[216:217]
	v_lshlrev_b32_e32 v216, 16, v250
	v_and_b32_e32 v217, 0xffff0000, v250
	v_pk_add_f32 v[218:219], v[218:219], v[216:217]
	v_lshlrev_b32_e32 v216, 16, v251
	v_and_b32_e32 v217, 0xffff0000, v251
	v_pk_add_f32 v[220:221], v[220:221], v[216:217]
	ds_read_b128 v[248:251], v163 offset:272
	s_waitcnt lgkmcnt(7)
	v_lshlrev_b32_e32 v216, 16, v252
	v_and_b32_e32 v217, 0xffff0000, v252
	v_pk_add_f32 v[106:107], v[106:107], v[216:217]
	v_lshlrev_b32_e32 v216, 16, v253
	v_and_b32_e32 v217, 0xffff0000, v253
	v_pk_add_f32 v[108:109], v[108:109], v[216:217]
	v_lshlrev_b32_e32 v216, 16, v254
	v_and_b32_e32 v217, 0xffff0000, v254
	v_pk_add_f32 v[218:219], v[218:219], v[216:217]
	v_lshlrev_b32_e32 v216, 16, v255
	v_and_b32_e32 v217, 0xffff0000, v255
	v_pk_add_f32 v[220:221], v[220:221], v[216:217]
	ds_read_b128 v[252:255], v163 offset:0
	s_waitcnt lgkmcnt(7)
	v_lshlrev_b32_e32 v216, 16, v222
	v_and_b32_e32 v217, 0xffff0000, v222
	v_pk_add_f32 v[106:107], v[106:107], v[216:217]
	v_lshlrev_b32_e32 v216, 16, v223
	v_and_b32_e32 v217, 0xffff0000, v223
	v_pk_add_f32 v[108:109], v[108:109], v[216:217]
	v_lshlrev_b32_e32 v216, 16, v224
	v_and_b32_e32 v217, 0xffff0000, v224
	v_pk_add_f32 v[218:219], v[218:219], v[216:217]
	v_lshlrev_b32_e32 v216, 16, v225
	v_and_b32_e32 v217, 0xffff0000, v225
	v_pk_add_f32 v[220:221], v[220:221], v[216:217]
	ds_read_b128 v[222:225], v163 offset:4112
	s_waitcnt lgkmcnt(7)
	v_lshlrev_b32_e32 v216, 16, v226
	v_and_b32_e32 v217, 0xffff0000, v226
	v_pk_add_f32 v[106:107], v[106:107], v[216:217]
	v_lshlrev_b32_e32 v216, 16, v227
	v_and_b32_e32 v217, 0xffff0000, v227
	v_pk_add_f32 v[108:109], v[108:109], v[216:217]
	v_lshlrev_b32_e32 v216, 16, v228
	v_and_b32_e32 v217, 0xffff0000, v228
	v_pk_add_f32 v[218:219], v[218:219], v[216:217]
	v_lshlrev_b32_e32 v216, 16, v229
	v_and_b32_e32 v217, 0xffff0000, v229
	v_pk_add_f32 v[220:221], v[220:221], v[216:217]
	ds_read_b128 v[226:229], v163 offset:3840
	s_waitcnt lgkmcnt(7)
	v_lshlrev_b32_e32 v216, 16, v230
	v_and_b32_e32 v217, 0xffff0000, v230
	v_pk_add_f32 v[106:107], v[106:107], v[216:217]
	v_lshlrev_b32_e32 v216, 16, v231
	v_and_b32_e32 v217, 0xffff0000, v231
	v_pk_add_f32 v[108:109], v[108:109], v[216:217]
	v_lshlrev_b32_e32 v216, 16, v232
	v_and_b32_e32 v217, 0xffff0000, v232
	v_pk_add_f32 v[218:219], v[218:219], v[216:217]
	v_lshlrev_b32_e32 v216, 16, v233
	v_and_b32_e32 v217, 0xffff0000, v233
	v_pk_add_f32 v[220:221], v[220:221], v[216:217]
	ds_read_b128 v[230:233], v163 offset:3568
	s_waitcnt lgkmcnt(7)
	v_lshlrev_b32_e32 v216, 16, v234
	v_and_b32_e32 v217, 0xffff0000, v234
	v_pk_add_f32 v[106:107], v[106:107], v[216:217]
	v_lshlrev_b32_e32 v216, 16, v235
	v_and_b32_e32 v217, 0xffff0000, v235
	v_pk_add_f32 v[108:109], v[108:109], v[216:217]
	v_lshlrev_b32_e32 v216, 16, v236
	v_and_b32_e32 v217, 0xffff0000, v236
	v_pk_add_f32 v[218:219], v[218:219], v[216:217]
	v_lshlrev_b32_e32 v216, 16, v237
	v_and_b32_e32 v217, 0xffff0000, v237
	v_pk_add_f32 v[220:221], v[220:221], v[216:217]
	ds_read_b128 v[234:237], v163 offset:3296
	s_waitcnt lgkmcnt(7)
	v_lshlrev_b32_e32 v216, 16, v238
	v_and_b32_e32 v217, 0xffff0000, v238
	v_pk_add_f32 v[106:107], v[106:107], v[216:217]
	v_lshlrev_b32_e32 v216, 16, v239
	v_and_b32_e32 v217, 0xffff0000, v239
	v_pk_add_f32 v[108:109], v[108:109], v[216:217]
	v_lshlrev_b32_e32 v216, 16, v240
	v_and_b32_e32 v217, 0xffff0000, v240
	v_pk_add_f32 v[218:219], v[218:219], v[216:217]
	v_lshlrev_b32_e32 v216, 16, v241
	v_and_b32_e32 v217, 0xffff0000, v241
	v_pk_add_f32 v[220:221], v[220:221], v[216:217]
	ds_read_b128 v[238:241], v163 offset:3024
	s_waitcnt lgkmcnt(7)
	v_lshlrev_b32_e32 v216, 16, v242
	v_and_b32_e32 v217, 0xffff0000, v242
	v_pk_add_f32 v[106:107], v[106:107], v[216:217]
	v_lshlrev_b32_e32 v216, 16, v243
	v_and_b32_e32 v217, 0xffff0000, v243
	v_pk_add_f32 v[108:109], v[108:109], v[216:217]
	v_lshlrev_b32_e32 v216, 16, v244
	v_and_b32_e32 v217, 0xffff0000, v244
	v_pk_add_f32 v[218:219], v[218:219], v[216:217]
	v_lshlrev_b32_e32 v216, 16, v245
	v_and_b32_e32 v217, 0xffff0000, v245
	v_pk_add_f32 v[220:221], v[220:221], v[216:217]
	ds_read_b128 v[242:245], v163 offset:2752
	s_waitcnt lgkmcnt(7)
	v_lshlrev_b32_e32 v216, 16, v248
	v_and_b32_e32 v217, 0xffff0000, v248
	v_pk_add_f32 v[106:107], v[106:107], v[216:217]
	v_lshlrev_b32_e32 v216, 16, v249
	v_and_b32_e32 v217, 0xffff0000, v249
	v_pk_add_f32 v[108:109], v[108:109], v[216:217]
	v_lshlrev_b32_e32 v216, 16, v250
	v_and_b32_e32 v217, 0xffff0000, v250
	v_pk_add_f32 v[218:219], v[218:219], v[216:217]
	v_lshlrev_b32_e32 v216, 16, v251
	v_and_b32_e32 v217, 0xffff0000, v251
	v_pk_add_f32 v[220:221], v[220:221], v[216:217]
	ds_read_b128 v[248:251], v163 offset:2480
	s_waitcnt lgkmcnt(7)
	v_lshlrev_b32_e32 v216, 16, v252
	v_and_b32_e32 v217, 0xffff0000, v252
	v_pk_add_f32 v[106:107], v[106:107], v[216:217]
	v_lshlrev_b32_e32 v216, 16, v253
	v_and_b32_e32 v217, 0xffff0000, v253
	v_pk_add_f32 v[108:109], v[108:109], v[216:217]
	v_lshlrev_b32_e32 v216, 16, v254
	v_and_b32_e32 v217, 0xffff0000, v254
	v_pk_add_f32 v[218:219], v[218:219], v[216:217]
	v_lshlrev_b32_e32 v216, 16, v255
	v_and_b32_e32 v217, 0xffff0000, v255
	v_pk_add_f32 v[220:221], v[220:221], v[216:217]
	ds_read_b128 v[252:255], v163 offset:2208
	v_fma_f32 v106, v159, v106, -v98
	v_fma_f32 v107, v159, v107, -v99
	v_fma_f32 v108, v159, v108, -v100
	v_fma_f32 v109, v159, v109, -v101
	v_fma_f32 v218, v159, v218, -v102
	v_fma_f32 v219, v159, v219, -v103
	v_fma_f32 v220, v159, v220, -v104
	v_fma_f32 v221, v159, v221, -v105
	v_cvt_pk_bf16_f32 v106, v106, v107
	v_cvt_pk_bf16_f32 v107, v108, v109
	v_cvt_pk_bf16_f32 v108, v218, v219
	v_cvt_pk_bf16_f32 v109, v220, v221
	s_and_saveexec_b64 s[28:29], s[6:7]
	s_cbranch_execz .Lpu0_0
	global_store_dwordx4 v[192:193], v[98:101], off offset:0
	global_store_dwordx4 v[192:193], v[102:105], off offset:16

.Lpu0_7:
	s_or_b64 exec, exec, s[28:29]
	s_waitcnt vmcnt(0)
	v_mfma_f32_32x32x16_bf16 v[2:17], v[106:109], v[82:85], v[2:17]
	v_mfma_f32_32x32x16_bf16 v[18:33], v[106:109], v[86:89], v[18:33]
	v_mfma_f32_32x32x16_bf16 v[34:49], v[106:109], v[90:93], v[34:49]
	v_mfma_f32_32x32x16_bf16 v[50:65], v[106:109], v[94:97], v[50:65]
	s_mov_b64 s[10:11], 0x10000
	v_lshl_add_u64 v[112:113], v[110:111], 0, s[10:11]
	s_mov_b64 s[10:11], 0x12000
	v_lshl_add_u64 v[114:115], v[110:111], 0, s[10:11]
	s_mov_b64 s[10:11], 0x14000
	v_lshl_add_u64 v[116:117], v[110:111], 0, s[10:11]
	s_mov_b64 s[10:11], 0x16000
	v_lshl_add_u64 v[118:119], v[110:111], 0, s[10:11]
	s_mov_b64 s[10:11], 0x8000
	v_lshl_add_u64 v[122:123], v[110:111], 0, s[10:11]
	s_mov_b64 s[10:11], 0xa000
	v_lshl_add_u64 v[124:125], v[110:111], 0, s[10:11]
	s_mov_b64 s[10:11], 0xc000
	v_lshl_add_u64 v[126:127], v[110:111], 0, s[10:11]
	s_mov_b64 s[10:11], 0xe000
	v_lshl_add_u64 v[128:129], v[110:111], 0, s[10:11]
	s_setprio 0
	s_branch .LBB0_338
